# phase C K-loop head back on a 64-byte boundary (alignment directive moved behind the per-tile DMA setup)
# baseline (speedup 1.0000x reference)
; #define TIDX512 launder_i((int)threadIdx.x)
; __device__ __forceinline__ void glds16(const bf16_t* g, char* l) { __builtin_amdgcn_global_load_lds((const unsigned*)g, (unsigned*)l, 16, 0, 0); }
; __device__ __forceinline__ void gemm_issue(const GemmSrc& g, int kt, int s, char* lds) {
;     const int tid = TIDX512, lane = tid & 63, wave = tid >> 6;
;     char* xdst = lds + s * 65536 + wave * 4096 + lane * 16;
;     char* wdst = xdst + 32768;
; #pragma unroll
;     for (int i = 0; i < 4; i++) {
;         const int d = (i & 1) ? g.dsw : 0;
;         glds16(g.xsrc + (size_t)i * 8 * g.ldx + kt * 64 + d, xdst + i * 1024);
;         glds16(g.wsrc + (size_t)i * 8 * g.ldw + kt * 64 + d, wdst + i * 1024);
;     }
; }
; __device__ __forceinline__ void gemm_prologue(const GemmSrc& g, char* lds) { gemm_issue(g, 0, 0, lds); }
; __device__ __forceinline__ void gemm_mainloop(f32x4 (&acc)[8][4], const GemmSrc& g, int K, char* lds) {
;     const int tid = TIDX512, lane = tid & 63, wave = tid >> 6;
;     const int wr = wave >> 2, wc = wave & 3, r = lane & 15, q = lane >> 4;
;     const int KT = K / 64;
;     const int rdo0 = r * 128 + ((q ^ (r >> 1)) * 16), rdo1 = r * 128 + (((4 + q) ^ (r >> 1)) * 16);
;     const int woff = 32768 + wc * 64 * 128, xoff = wr * 128 * 128;
; __device__ __forceinline__ void zero_acc(f32x4 (&acc)[8][4]) {
; #pragma unroll
;     for (int a = 0; a < 8; a++)
; #pragma unroll
;         for (int b = 0; b < 4; b++) acc[a][b] = (f32x4){0.f, 0.f, 0.f, 0.f};
; }
.LBB0_298:
	s_andn2_b64 vcc, exec, s[8:9]
	s_mov_b64 s[8:9], -1
	s_cbranch_vccnz .LBB0_290
	v_mov_b32_e32 v0, v158
	s_lshl_b32 s82, s74, 8
	v_ashrrev_i32_e32 v1, 1, v0
	v_and_b32_e32 v12, 0xffffffe0, v1
	v_bfe_u32 v1, v0, 4, 2
	v_and_b32_e32 v3, 7, v0
	v_bitop3_b32 v4, v1, v0, 7 bitop3:0x78
	v_bitop3_b32 v5, v1, v3, 4 bitop3:0x36
	v_lshlrev_b32_e32 v128, 4, v4
	v_sub_u32_e32 v4, v5, v4
	v_mov_b32_e32 v5, v158
	v_bfe_u32 v13, v0, 3, 3
	v_or_b32_e32 v2, v12, v13
	v_lshlrev_b32_e32 v6, 6, v5
	v_lshlrev_b32_e32 v5, 4, v5
	s_lshl_b32 s44, s75, 8
	v_add_u32_e32 v0, s82, v2
	v_and_b32_e32 v5, 0x3f0, v5
	v_ashrrev_i32_e32 v1, 31, v0
	v_add_u32_e32 v2, s44, v2
	v_and_or_b32 v14, v6, s51, v5
	v_lshlrev_b64 v[0:1], 11, v[0:1]
	v_ashrrev_i32_e32 v3, 31, v2
	v_lshlrev_b32_e32 v4, 3, v4
	v_add_u32_e32 v5, 0x8000, v14
	v_readfirstlane_b32 s0, v14
	v_lshl_add_u64 v[0:1], s[14:15], 0, v[0:1]
	v_lshlrev_b64 v[2:3], 11, v[2:3]
	s_mov_b32 m0, s0
	v_readfirstlane_b32 s0, v5
	v_ashrrev_i32_e32 v5, 31, v4
	v_lshl_add_u64 v[0:1], v[0:1], 0, v[128:129]
	v_lshl_add_u64 v[2:3], s[16:17], 0, v[2:3]
	v_lshlrev_b64 v[4:5], 1, v[4:5]
	v_or_b32_e32 v10, 0x400, v14
	v_lshl_add_u64 v[2:3], v[2:3], 0, v[128:129]
	global_load_lds_dwordx4 v[0:1], off
	s_mov_b32 m0, s0
	v_lshl_add_u64 v[6:7], v[0:1], 0, v[4:5]
	v_readfirstlane_b32 s0, v10
	global_load_lds_dwordx4 v[2:3], off
	v_lshl_add_u64 v[8:9], v[6:7], 0, s[20:21]
	s_mov_b32 m0, s0
	v_add_u32_e32 v15, 0x8400, v14
	global_load_lds_dwordx4 v[8:9], off
	v_lshl_add_u64 v[8:9], v[2:3], 0, v[4:5]
	v_readfirstlane_b32 s0, v15
	v_lshl_add_u64 v[10:11], v[8:9], 0, s[20:21]
	s_mov_b32 m0, s0
	v_lshl_add_u64 v[0:1], v[0:1], 0, s[22:23]
	global_load_lds_dwordx4 v[10:11], off
	v_or_b32_e32 v10, 0x800, v14
	s_mov_b64 s[8:9], 0
	v_readfirstlane_b32 s0, v10
	s_mov_b32 m0, s0
	s_nop 0
	global_load_lds_dwordx4 v[0:1], off
	v_lshl_add_u64 v[0:1], v[2:3], 0, s[22:23]
	v_add_u32_e32 v2, 0x8800, v14
	s_nop 0
	v_readfirstlane_b32 s0, v2
	v_or_b32_e32 v2, 0xc00, v14
	s_mov_b32 m0, s0
	v_readfirstlane_b32 s0, v2
	v_add_u32_e32 v2, 0x8c00, v14
	global_load_lds_dwordx4 v[0:1], off
	v_lshl_add_u64 v[0:1], v[6:7], 0, s[24:25]
	s_mov_b32 m0, s0
	v_readfirstlane_b32 s0, v2
	global_load_lds_dwordx4 v[0:1], off
	v_lshl_add_u64 v[0:1], v[8:9], 0, s[24:25]
	s_mov_b32 m0, s0
	s_mov_b32 s0, 0x10000
	global_load_lds_dwordx4 v[0:1], off
	v_mov_b32_e32 v0, v158
	s_nop 0
	v_and_b32_e32 v1, 15, v0
	v_lshrrev_b32_e32 v2, 4, v0
	v_bfe_u32 v6, v0, 1, 3
	v_bfe_u32 v3, v0, 4, 2
	v_lshlrev_b32_e32 v1, 7, v1
	v_bitop3_b32 v2, v2, v6, 3 bitop3:0x6c
	v_lshl_or_b32 v142, v2, 4, v1
	v_bitop3_b32 v2, v3, v6, 4 bitop3:0x36
	v_lshl_or_b32 v133, v2, 4, v1
	v_lshlrev_b32_e32 v1, 7, v0
	v_lshlrev_b32_e32 v0, 6, v0
	v_and_b32_e32 v143, 0xffffc000, v0
	v_or_b32_e32 v0, s82, v13
	v_add_u32_e32 v0, v0, v12
	v_or_b32_e32 v2, s44, v13
	v_and_b32_e32 v144, 0x6000, v1
	v_ashrrev_i32_e32 v1, 31, v0
	v_add_u32_e32 v2, v2, v12
	v_lshlrev_b64 v[0:1], 11, v[0:1]
	v_ashrrev_i32_e32 v3, 31, v2
	v_or_b32_e32 v0, v0, v128
	v_lshlrev_b64 v[2:3], 11, v[2:3]
	v_lshl_add_u64 v[134:135], s[10:11], 0, v[0:1]
	v_or_b32_e32 v2, v2, v128
	v_lshl_add_u64 v[0:1], v[0:1], 0, v[4:5]
	v_lshl_add_u64 v[138:139], s[10:11], 0, v[0:1]
	v_lshl_add_u64 v[0:1], v[2:3], 0, v[4:5]
	v_lshl_add_u64 v[140:141], s[10:11], 0, v[0:1]
	v_mov_b32_e32 v0, 0
	v_lshl_add_u64 v[136:137], s[10:11], 0, v[2:3]
	v_mov_b32_e32 v1, v0
	v_mov_b32_e32 v2, v0
	v_mov_b32_e32 v3, v0
	v_mov_b32_e32 v4, v0
	v_mov_b32_e32 v5, v0
	v_mov_b32_e32 v6, v0
	v_mov_b32_e32 v7, v0
	v_mov_b32_e32 v8, v0
	v_mov_b32_e32 v9, v0
	v_mov_b32_e32 v10, v0
	v_mov_b32_e32 v11, v0
	v_mov_b32_e32 v12, v0
	v_mov_b32_e32 v13, v0
	v_mov_b32_e32 v14, v0
	v_mov_b32_e32 v15, v0
	v_mov_b32_e32 v16, v0
	v_mov_b32_e32 v17, v0
	v_mov_b32_e32 v18, v0
	v_mov_b32_e32 v19, v0
	v_mov_b32_e32 v20, v0
	v_mov_b32_e32 v21, v0
	v_mov_b32_e32 v22, v0
	v_mov_b32_e32 v23, v0
	v_mov_b32_e32 v24, v0
	v_mov_b32_e32 v25, v0
	v_mov_b32_e32 v26, v0
	v_mov_b32_e32 v27, v0
	v_mov_b32_e32 v28, v0
	v_mov_b32_e32 v29, v0
	v_mov_b32_e32 v30, v0
	v_mov_b32_e32 v31, v0
	v_mov_b32_e32 v32, v0
	v_mov_b32_e32 v33, v0
	v_mov_b32_e32 v34, v0
	v_mov_b32_e32 v35, v0
	v_mov_b32_e32 v36, v0
	v_mov_b32_e32 v37, v0
	v_mov_b32_e32 v38, v0
	v_mov_b32_e32 v39, v0
	v_mov_b32_e32 v40, v0
	v_mov_b32_e32 v41, v0
	v_mov_b32_e32 v42, v0
	v_mov_b32_e32 v43, v0
	v_mov_b32_e32 v44, v0
	v_mov_b32_e32 v45, v0
	v_mov_b32_e32 v46, v0
	v_mov_b32_e32 v47, v0
	v_mov_b32_e32 v48, v0
	v_mov_b32_e32 v49, v0
	v_mov_b32_e32 v50, v0
	v_mov_b32_e32 v51, v0
	v_mov_b32_e32 v52, v0
	v_mov_b32_e32 v53, v0
	v_mov_b32_e32 v54, v0
	v_mov_b32_e32 v55, v0
	v_mov_b32_e32 v56, v0
	v_mov_b32_e32 v57, v0
	v_mov_b32_e32 v58, v0
	v_mov_b32_e32 v59, v0
	v_mov_b32_e32 v60, v0
	v_mov_b32_e32 v61, v0
	v_mov_b32_e32 v62, v0
	v_mov_b32_e32 v63, v0
	v_mov_b32_e32 v64, v0
	v_mov_b32_e32 v65, v0
	v_mov_b32_e32 v66, v0
	v_mov_b32_e32 v67, v0
	v_mov_b32_e32 v68, v0
	v_mov_b32_e32 v69, v0
	v_mov_b32_e32 v70, v0
	v_mov_b32_e32 v71, v0
	v_mov_b32_e32 v72, v0
	v_mov_b32_e32 v73, v0
	v_mov_b32_e32 v74, v0
	v_mov_b32_e32 v75, v0
	v_mov_b32_e32 v76, v0
	v_mov_b32_e32 v77, v0
	v_mov_b32_e32 v78, v0
	v_mov_b32_e32 v79, v0
	v_mov_b32_e32 v80, v0
	v_mov_b32_e32 v81, v0
	v_mov_b32_e32 v82, v0
	v_mov_b32_e32 v83, v0
	v_mov_b32_e32 v84, v0
	v_mov_b32_e32 v85, v0
	v_mov_b32_e32 v86, v0
	v_mov_b32_e32 v87, v0
	v_mov_b32_e32 v88, v0
	v_mov_b32_e32 v89, v0
	v_mov_b32_e32 v90, v0
	v_mov_b32_e32 v91, v0
	v_mov_b32_e32 v92, v0
	v_mov_b32_e32 v93, v0
	v_mov_b32_e32 v94, v0
	v_mov_b32_e32 v95, v0
	v_mov_b32_e32 v96, v0
	v_mov_b32_e32 v97, v0
	v_mov_b32_e32 v98, v0
	v_mov_b32_e32 v99, v0
	v_mov_b32_e32 v100, v0
	v_mov_b32_e32 v101, v0
	v_mov_b32_e32 v102, v0
	v_mov_b32_e32 v103, v0
	v_mov_b32_e32 v104, v0
	v_mov_b32_e32 v105, v0
	v_mov_b32_e32 v106, v0
	v_mov_b32_e32 v107, v0
	v_mov_b32_e32 v108, v0
	v_mov_b32_e32 v109, v0
	v_mov_b32_e32 v110, v0
	v_mov_b32_e32 v111, v0
	v_mov_b32_e32 v112, v0
	v_mov_b32_e32 v113, v0
	v_mov_b32_e32 v114, v0
	v_mov_b32_e32 v115, v0
	v_mov_b32_e32 v116, v0
	v_mov_b32_e32 v117, v0
	v_mov_b32_e32 v118, v0
	v_mov_b32_e32 v119, v0
	v_mov_b32_e32 v120, v0
	v_mov_b32_e32 v121, v0
	v_mov_b32_e32 v122, v0
	v_mov_b32_e32 v123, v0
	v_mov_b32_e32 v124, v0
	v_mov_b32_e32 v125, v0
	v_mov_b32_e32 v126, v0
	v_mov_b32_e32 v127, v0
	v_lshlrev_b32_e32 v208, 6, v158
	v_and_b32_e32 v208, 0xfffff000, v208
	v_lshlrev_b32_e32 v209, 4, v158
	v_and_or_b32 v208, v209, s50, v208
	s_nop 0
	v_readfirstlane_b32 s86, v208
	.p2alignl 6, 3212836864
